# nt hint also on P7 epilogue residual loads and output stores
# baseline (speedup 1.0000x reference)
;   DI void epi(f32x4 (&acc)[2][2][4][2], const GUnit& u) const { epi_inproj<REG>(p, acc, u.pm, u.pn, shm); }
;   DI void epi(f32x4 (&acc)[2][2][4][2], const GUnit& u) const { if (emode != 2 || p.x == nullptr) epi_gu(p, acc, u.pm, u.pn, emode); }
;   DI void epi(f32x4 (&acc)[2][2][4][2], const GUnit& u) const {
;     int tid_ = threadIdx.x; asm volatile("" : "+v"(tid_)); const int tid = tid_, wid = tid >> 6, lane = tid & 63, wr = wid >> 2, wc = wid & 3, fr = lane & 15, fq = lane >> 4;
;     const long cbase = ((long)u.pm * 256 + 64 * wr + fr) * 1024 + u.pn * 256 + 32 * wc + 4 * fq;
; #pragma unroll
;     for (int ai = 0; ai < 2; ++ai) {
;       f32x4 pre[4][2][2];
; #pragma unroll
;       for (int m = 0; m < 4; ++m)
; #pragma unroll
;         for (int bj = 0; bj < 2; ++bj)
; #pragma unroll
;           for (int n = 0; n < 2; ++n) pre[m][bj][n] = *(const f32x4*)(p.out + cbase + (long)(128 * ai + 16 * m) * 1024 + 128 * bj + 16 * n);
;       asm volatile("" ::: "memory");
; #pragma unroll
;       for (int m = 0; m < 4; ++m)
; #pragma unroll
;         for (int bj = 0; bj < 2; ++bj)
; #pragma unroll
;           for (int n = 0; n < 2; ++n) *(f32x4*)(outw + cbase + (long)(128 * ai + 16 * m) * 1024 + 128 * bj + 16 * n) = pre[m][bj][n] + acc[ai][bj][m][n];
;       asm volatile("" ::: "memory");
;     }
;   }
.LBB0_1146:
	v_mov_b32_e32 v145, v194
	s_ashr_i32 s15, s14, 31
	v_ashrrev_i32_e32 v136, 2, v145
	v_and_b32_e32 v146, 0xffffffc0, v136
	s_lshl_b64 s[14:15], s[14:15], 8
	v_ashrrev_i32_e32 v147, 31, v146
	v_lshl_add_u64 v[146:147], s[14:15], 0, v[146:147]
	v_and_or_b32 v146, v145, 15, v146
	s_lshl_b32 s14, s66, 8
	v_lshlrev_b64 v[146:147], 12, v[146:147]
	s_ashr_i32 s15, s14, 31
	v_lshl_add_u64 v[146:147], s[24:25], 0, v[146:147]
	v_lshlrev_b32_e32 v136, 1, v145
	v_lshl_add_u64 v[146:147], s[14:15], 2, v[146:147]
	v_and_b32_e32 v136, 0x180, v136
	v_lshl_add_u64 v[146:147], v[146:147], 0, v[136:137]
	v_and_b32_e32 v136, 48, v145
	v_lshl_add_u64 v[212:213], v[146:147], 0, v[136:137]
	v_add_co_u32_e32 v214, vcc, s44, v212
	global_load_dwordx4 v[146:149], v[212:213], off nt
	global_load_dwordx4 v[150:153], v[212:213], off offset:64 nt
	global_load_dwordx4 v[154:157], v[212:213], off offset:512 nt
	global_load_dwordx4 v[158:161], v[212:213], off offset:576 nt
	v_addc_co_u32_e32 v215, vcc, 0, v213, vcc
	v_add_co_u32_e32 v216, vcc, s58, v212
	global_load_dwordx4 v[162:165], v[214:215], off nt
	global_load_dwordx4 v[166:169], v[214:215], off offset:64 nt
	global_load_dwordx4 v[170:173], v[214:215], off offset:512 nt
	global_load_dwordx4 v[174:177], v[214:215], off offset:576 nt
	v_addc_co_u32_e32 v217, vcc, 0, v213, vcc
	v_add_co_u32_e32 v218, vcc, s59, v212
	global_load_dwordx4 v[178:181], v[216:217], off nt
	global_load_dwordx4 v[182:185], v[216:217], off offset:64 nt
	global_load_dwordx4 v[186:189], v[216:217], off offset:512 nt
	global_load_dwordx4 v[190:193], v[216:217], off offset:576 nt
	v_addc_co_u32_e32 v219, vcc, 0, v213, vcc
	global_load_dwordx4 v[196:199], v[218:219], off nt
	global_load_dwordx4 v[200:203], v[218:219], off offset:64 nt
	global_load_dwordx4 v[204:207], v[218:219], off offset:512 nt
	global_load_dwordx4 v[208:211], v[218:219], off offset:576 nt
	v_add_co_u32_e32 v222, vcc, s60, v212
	s_nop 1
	v_addc_co_u32_e32 v223, vcc, 0, v213, vcc
	v_add_co_u32_e32 v224, vcc, s61, v212
	s_nop 1
	v_addc_co_u32_e32 v225, vcc, 0, v213, vcc
	v_add_co_u32_e32 v226, vcc, s62, v212
	s_nop 1
	v_addc_co_u32_e32 v227, vcc, 0, v213, vcc
	v_add_co_u32_e32 v228, vcc, s63, v212
	s_nop 1
	v_addc_co_u32_e32 v229, vcc, 0, v213, vcc
	s_waitcnt vmcnt(0)
	v_pk_add_f32 v[124:125], v[124:125], v[146:147]
	v_pk_add_f32 v[126:127], v[126:127], v[148:149]
	v_pk_add_f32 v[120:121], v[120:121], v[150:151]
	v_pk_add_f32 v[122:123], v[122:123], v[152:153]
	v_pk_add_f32 v[116:117], v[116:117], v[154:155]
	v_pk_add_f32 v[118:119], v[118:119], v[156:157]
	v_pk_add_f32 v[108:109], v[108:109], v[158:159]
	v_pk_add_f32 v[110:111], v[110:111], v[160:161]
	v_pk_add_f32 v[112:113], v[112:113], v[162:163]
	v_pk_add_f32 v[114:115], v[114:115], v[164:165]
	v_pk_add_f32 v[104:105], v[104:105], v[166:167]
	v_pk_add_f32 v[106:107], v[106:107], v[168:169]
	v_pk_add_f32 v[96:97], v[96:97], v[170:171]
	v_pk_add_f32 v[98:99], v[98:99], v[172:173]
	v_pk_add_f32 v[88:89], v[88:89], v[174:175]
	v_pk_add_f32 v[90:91], v[90:91], v[176:177]
	v_pk_add_f32 v[100:101], v[100:101], v[178:179]
	v_pk_add_f32 v[102:103], v[102:103], v[180:181]
	v_pk_add_f32 v[92:93], v[92:93], v[182:183]
	v_pk_add_f32 v[94:95], v[94:95], v[184:185]
	v_pk_add_f32 v[80:81], v[80:81], v[186:187]
	v_pk_add_f32 v[82:83], v[82:83], v[188:189]
	v_pk_add_f32 v[72:73], v[72:73], v[190:191]
	v_pk_add_f32 v[74:75], v[74:75], v[192:193]
	v_pk_add_f32 v[84:85], v[84:85], v[196:197]
	v_pk_add_f32 v[86:87], v[86:87], v[198:199]
	v_pk_add_f32 v[76:77], v[76:77], v[200:201]
	v_pk_add_f32 v[78:79], v[78:79], v[202:203]
	v_pk_add_f32 v[68:69], v[68:69], v[204:205]
	v_pk_add_f32 v[70:71], v[70:71], v[206:207]
	v_pk_add_f32 v[64:65], v[64:65], v[208:209]
	v_pk_add_f32 v[66:67], v[66:67], v[210:211]
	global_load_dwordx4 v[146:149], v[222:223], off nt
	global_load_dwordx4 v[150:153], v[222:223], off offset:64 nt
	global_load_dwordx4 v[154:157], v[222:223], off offset:512 nt
	global_load_dwordx4 v[158:161], v[222:223], off offset:576 nt
	global_load_dwordx4 v[162:165], v[224:225], off nt
	global_load_dwordx4 v[166:169], v[224:225], off offset:64 nt
	global_load_dwordx4 v[170:173], v[224:225], off offset:512 nt
	global_load_dwordx4 v[174:177], v[224:225], off offset:576 nt
	global_load_dwordx4 v[178:181], v[226:227], off nt
	global_load_dwordx4 v[182:185], v[226:227], off offset:64 nt
	global_load_dwordx4 v[186:189], v[226:227], off offset:512 nt
	global_load_dwordx4 v[190:193], v[226:227], off offset:576 nt
	global_load_dwordx4 v[196:199], v[228:229], off nt
	global_load_dwordx4 v[200:203], v[228:229], off offset:64 nt
	global_load_dwordx4 v[204:207], v[228:229], off offset:512 nt
	global_load_dwordx4 v[208:211], v[228:229], off offset:576 nt
	global_store_dwordx4 v[212:213], v[124:127], off nt
	global_store_dwordx4 v[212:213], v[120:123], off offset:64 nt
	global_store_dwordx4 v[212:213], v[116:119], off offset:512 nt
	global_store_dwordx4 v[212:213], v[108:111], off offset:576 nt
	global_store_dwordx4 v[214:215], v[112:115], off nt
	global_store_dwordx4 v[214:215], v[104:107], off offset:64 nt
	global_store_dwordx4 v[214:215], v[96:99], off offset:512 nt
	global_store_dwordx4 v[214:215], v[88:91], off offset:576 nt
	global_store_dwordx4 v[216:217], v[100:103], off nt
	global_store_dwordx4 v[216:217], v[92:95], off offset:64 nt
	global_store_dwordx4 v[216:217], v[80:83], off offset:512 nt
	global_store_dwordx4 v[216:217], v[72:75], off offset:576 nt
	global_store_dwordx4 v[218:219], v[84:87], off nt
	global_store_dwordx4 v[218:219], v[76:79], off offset:64 nt
	global_store_dwordx4 v[218:219], v[68:71], off offset:512 nt
	global_store_dwordx4 v[218:219], v[64:67], off offset:576 nt
	s_andn2_b64 vcc, exec, s[12:13]
	s_mov_b64 s[12:13], -1
	s_waitcnt vmcnt(31)
;   DI void epi(f32x4 (&acc)[2][2][4][2], const GUnit& u) const {
;     ...
;       for (int m = 0; m < 4; ++m)
; #pragma unroll
;         for (int bj = 0; bj < 2; ++bj)
; #pragma unroll
;           for (int n = 0; n < 2; ++n) *(f32x4*)(outw + cbase + (long)(128 * ai + 16 * m) * 1024 + 128 * bj + 16 * n) = pre[m][bj][n] + acc[ai][bj][m][n];
;       asm volatile("" ::: "memory");
;     }
;   }
	v_pk_add_f32 v[62:63], v[62:63], v[148:149]
	v_pk_add_f32 v[60:61], v[60:61], v[146:147]
	s_waitcnt vmcnt(30)
	v_pk_add_f32 v[58:59], v[58:59], v[152:153]
	v_pk_add_f32 v[56:57], v[56:57], v[150:151]
	s_waitcnt vmcnt(29)
	v_pk_add_f32 v[50:51], v[50:51], v[156:157]
	v_pk_add_f32 v[48:49], v[48:49], v[154:155]
	s_waitcnt vmcnt(28)
	v_pk_add_f32 v[42:43], v[42:43], v[160:161]
	v_pk_add_f32 v[40:41], v[40:41], v[158:159]
	s_waitcnt vmcnt(27)
	v_pk_add_f32 v[54:55], v[54:55], v[164:165]
	v_pk_add_f32 v[52:53], v[52:53], v[162:163]
	s_waitcnt vmcnt(26)
	v_pk_add_f32 v[46:47], v[46:47], v[168:169]
	v_pk_add_f32 v[44:45], v[44:45], v[166:167]
	s_waitcnt vmcnt(25)
	v_pk_add_f32 v[34:35], v[34:35], v[172:173]
	v_pk_add_f32 v[32:33], v[32:33], v[170:171]
	s_waitcnt vmcnt(24)
	v_pk_add_f32 v[26:27], v[26:27], v[176:177]
	v_pk_add_f32 v[24:25], v[24:25], v[174:175]
	s_waitcnt vmcnt(23)
	v_pk_add_f32 v[38:39], v[38:39], v[180:181]
	v_pk_add_f32 v[36:37], v[36:37], v[178:179]
	s_waitcnt vmcnt(22)
	v_pk_add_f32 v[30:31], v[30:31], v[184:185]
	v_pk_add_f32 v[28:29], v[28:29], v[182:183]
	s_waitcnt vmcnt(21)
	v_pk_add_f32 v[18:19], v[18:19], v[188:189]
	v_pk_add_f32 v[16:17], v[16:17], v[186:187]
	s_waitcnt vmcnt(20)
	v_pk_add_f32 v[10:11], v[10:11], v[192:193]
	v_pk_add_f32 v[8:9], v[8:9], v[190:191]
	s_waitcnt vmcnt(19)
	v_pk_add_f32 v[22:23], v[22:23], v[198:199]
	v_pk_add_f32 v[20:21], v[20:21], v[196:197]
	s_waitcnt vmcnt(18)
	v_pk_add_f32 v[14:15], v[14:15], v[202:203]
	v_pk_add_f32 v[12:13], v[12:13], v[200:201]
	s_waitcnt vmcnt(17)
	v_pk_add_f32 v[6:7], v[6:7], v[206:207]
	v_pk_add_f32 v[4:5], v[4:5], v[204:205]
	s_waitcnt vmcnt(16)
	v_pk_add_f32 v[2:3], v[2:3], v[210:211]
	v_pk_add_f32 v[0:1], v[0:1], v[208:209]
	global_store_dwordx4 v[222:223], v[60:63], off nt
	global_store_dwordx4 v[222:223], v[56:59], off offset:64 nt
	global_store_dwordx4 v[222:223], v[48:51], off offset:512 nt
	global_store_dwordx4 v[222:223], v[40:43], off offset:576 nt
	global_store_dwordx4 v[224:225], v[52:55], off nt
	global_store_dwordx4 v[224:225], v[44:47], off offset:64 nt
	global_store_dwordx4 v[224:225], v[32:35], off offset:512 nt
	global_store_dwordx4 v[224:225], v[24:27], off offset:576 nt
	global_store_dwordx4 v[226:227], v[36:39], off nt
	global_store_dwordx4 v[226:227], v[28:31], off offset:64 nt
	global_store_dwordx4 v[226:227], v[16:19], off offset:512 nt
	global_store_dwordx4 v[226:227], v[8:11], off offset:576 nt
	global_store_dwordx4 v[228:229], v[20:23], off nt
	global_store_dwordx4 v[228:229], v[12:15], off offset:64 nt
	global_store_dwordx4 v[228:229], v[4:7], off offset:512 nt
	global_store_dwordx4 v[228:229], v[0:3], off offset:576 nt
	s_cbranch_vccnz .LBB0_1131
	s_andn2_b64 vcc, exec, s[0:1]
	s_cbranch_vccnz .LBB0_1130
	s_barrier
	s_branch .LBB0_1130
